# P7: compiler tile-top store-drain vmcnt(0) removed so the preloaded ss loads overlap the drain (as in P1/P3)
# baseline (speedup 1.0000x reference)
; template <class Epi>
; __device__ __forceinline__ void gemm_phase(LAS unsigned char* lds, const Gemm g, const StaticOrder& S, const Epi& E) {
;     ...
;         const bool has_next = S.next(ui + 1, nxt);
;         const char* nA = has_next ? (const char*)g.A + (size_t)nxt.pm * tstepA : cA; const char* nB = has_next ? (const char*)g.Bt + (size_t)nxt.pn * tstepB : cB;
;     ...
;         for (int a = 0; a < 2; ++a)
; #pragma unroll
;             for (int b = 0; b < 2; ++b)
; #pragma unroll
;                 for (int m = 0; m < 4; ++m)
; #pragma unroll
;                     for (int n = 0; n < 2; ++n) acc[a][b][m][n] = (f32x4){0.f, 0.f, 0.f, 0.f};
;         cur = nxt; cA = nA; cB = nB; ++ui;
;     __device__ __forceinline__ void operator()(const Acc& acc, const Unit& u, int wr, int wc, int fr, int fq) const {
;         float ssv[2][4];
; #pragma unroll
;         for (int ai = 0; ai < 2; ++ai)
; #pragma unroll
;             for (int m = 0; m < 4; ++m) ssv[ai][m] = ss[u.pm * 256 + ai * 128 + wr * 64 + m * 16 + fr];
.LBB0_1731:
	s_ashr_i32 s21, s20, 31
	s_lshl_b64 s[22:23], s[20:21], 19
	s_add_u32 s22, s18, s22
	s_addc_u32 s23, s19, s23
	s_and_b64 s[24:25], s[6:7], exec
	s_cselect_b32 s21, s23, s27
	s_cselect_b32 s51, s22, s26
	s_ashr_i32 s15, s14, 31
	s_lshl_b64 s[24:25], s[14:15], 19
	v_readlane_b32 s30, v254, 43
	v_readlane_b32 s31, v254, 44
	s_add_u32 s24, s30, s24
	s_addc_u32 s25, s31, s25
	s_and_b64 s[30:31], s[6:7], exec
	s_cselect_b32 s15, s25, s29
	s_cselect_b32 s52, s24, s28
	s_add_u32 s26, s26, 0x40080
	s_addc_u32 s27, s27, 0
	s_add_u32 s53, s28, 0x100
	v_mov_b32_e32 v0, 0
	s_addc_u32 s54, s29, 0
	s_mov_b32 s55, -2
	v_mov_b32_e32 v1, v0
	v_mov_b32_e32 v2, v0
	v_mov_b32_e32 v3, v0
	v_mov_b32_e32 v8, v0
	v_mov_b32_e32 v9, v0
	v_mov_b32_e32 v10, v0
	v_mov_b32_e32 v11, v0
	v_mov_b32_e32 v16, v0
	v_mov_b32_e32 v17, v0
	v_mov_b32_e32 v18, v0
	v_mov_b32_e32 v19, v0
	v_mov_b32_e32 v24, v0
	v_mov_b32_e32 v25, v0
	v_mov_b32_e32 v26, v0
	v_mov_b32_e32 v27, v0
	v_mov_b32_e32 v32, v0
	v_mov_b32_e32 v33, v0
	v_mov_b32_e32 v34, v0
	v_mov_b32_e32 v35, v0
	v_mov_b32_e32 v40, v0
	v_mov_b32_e32 v41, v0
	v_mov_b32_e32 v42, v0
	v_mov_b32_e32 v43, v0
	v_mov_b32_e32 v48, v0
	v_mov_b32_e32 v49, v0
	v_mov_b32_e32 v50, v0
	v_mov_b32_e32 v51, v0
	v_mov_b32_e32 v56, v0
	v_mov_b32_e32 v57, v0
	v_mov_b32_e32 v58, v0
	v_mov_b32_e32 v59, v0
	v_mov_b32_e32 v4, v0
	v_mov_b32_e32 v5, v0
	v_mov_b32_e32 v6, v0
	v_mov_b32_e32 v7, v0
	v_mov_b32_e32 v12, v0
	v_mov_b32_e32 v13, v0
	v_mov_b32_e32 v14, v0
	v_mov_b32_e32 v15, v0
	v_mov_b32_e32 v20, v0
	v_mov_b32_e32 v21, v0
	v_mov_b32_e32 v22, v0
	v_mov_b32_e32 v23, v0
	v_mov_b32_e32 v28, v0
	v_mov_b32_e32 v29, v0
	v_mov_b32_e32 v30, v0
	v_mov_b32_e32 v31, v0
	v_mov_b32_e32 v36, v0
	v_mov_b32_e32 v37, v0
	v_mov_b32_e32 v38, v0
	v_mov_b32_e32 v39, v0
	v_mov_b32_e32 v44, v0
	v_mov_b32_e32 v45, v0
	v_mov_b32_e32 v46, v0
	v_mov_b32_e32 v47, v0
	v_mov_b32_e32 v52, v0
	v_mov_b32_e32 v53, v0
	v_mov_b32_e32 v54, v0
	v_mov_b32_e32 v55, v0
	v_mov_b32_e32 v60, v0
	v_mov_b32_e32 v61, v0
	v_mov_b32_e32 v62, v0
	v_mov_b32_e32 v63, v0
	s_nop 0
	v_mov_b32_e32 v64, v0
	v_mov_b32_e32 v65, v0
	v_mov_b32_e32 v66, v0
	v_mov_b32_e32 v67, v0
	v_mov_b32_e32 v72, v0
	v_mov_b32_e32 v73, v0
	v_mov_b32_e32 v74, v0
	v_mov_b32_e32 v75, v0
	v_mov_b32_e32 v80, v0
	v_mov_b32_e32 v81, v0
	v_mov_b32_e32 v82, v0
	v_mov_b32_e32 v83, v0
	v_mov_b32_e32 v88, v0
	v_mov_b32_e32 v89, v0
	v_mov_b32_e32 v90, v0
	v_mov_b32_e32 v91, v0
	v_mov_b32_e32 v96, v0
	v_mov_b32_e32 v97, v0
	v_mov_b32_e32 v98, v0
	v_mov_b32_e32 v99, v0
	v_mov_b32_e32 v104, v0
	v_mov_b32_e32 v105, v0
	v_mov_b32_e32 v106, v0
	v_mov_b32_e32 v107, v0
	v_mov_b32_e32 v112, v0
	v_mov_b32_e32 v113, v0
	v_mov_b32_e32 v114, v0
	v_mov_b32_e32 v115, v0
	v_mov_b32_e32 v120, v0
	v_mov_b32_e32 v121, v0
	v_mov_b32_e32 v122, v0
	v_mov_b32_e32 v123, v0
	v_mov_b32_e32 v68, v0
	v_mov_b32_e32 v69, v0
	v_mov_b32_e32 v70, v0
	v_mov_b32_e32 v71, v0
	v_mov_b32_e32 v76, v0
	v_mov_b32_e32 v77, v0
	v_mov_b32_e32 v78, v0
	v_mov_b32_e32 v79, v0
	v_mov_b32_e32 v84, v0
	v_mov_b32_e32 v85, v0
	v_mov_b32_e32 v86, v0
	v_mov_b32_e32 v87, v0
	v_mov_b32_e32 v92, v0
	v_mov_b32_e32 v93, v0
	v_mov_b32_e32 v94, v0
	v_mov_b32_e32 v95, v0
	v_mov_b32_e32 v100, v0
	v_mov_b32_e32 v101, v0
	v_mov_b32_e32 v102, v0
	v_mov_b32_e32 v103, v0
	v_mov_b32_e32 v108, v0
	v_mov_b32_e32 v109, v0
	v_mov_b32_e32 v110, v0
	v_mov_b32_e32 v111, v0
	v_mov_b32_e32 v116, v0
	v_mov_b32_e32 v117, v0
	v_mov_b32_e32 v118, v0
	v_mov_b32_e32 v119, v0
	v_mov_b32_e32 v124, v0
	v_mov_b32_e32 v125, v0
	v_mov_b32_e32 v126, v0
	v_mov_b32_e32 v127, v0
	s_lshl_b32 s85, s0, 8
	s_add_i32 s85, s85, s40
	v_or_b32_e32 v250, s85, v144
	v_ashrrev_i32_e32 v251, 31, v250
	v_lshl_add_u64 v[252:253], v[250:251], 2, s[16:17]
	global_load_dword v235, v[252:253], off
	global_load_dword v236, v[252:253], off offset:64
	global_load_dword v237, v[252:253], off offset:128
	global_load_dword v238, v[252:253], off offset:192
	global_load_dword v239, v[252:253], off offset:512
	global_load_dword v240, v[252:253], off offset:576
	global_load_dword v241, v[252:253], off offset:640
	global_load_dword v242, v[252:253], off offset:704
